# GEMM unit loops (phases 2, 8, 10, 11): the 128 accumulator VGPRs are zeroed with 64 v_mov_b64 inline-0 moves instead of 127 v_mov_b32 copies
# speedup vs baseline: 1.0234x; 1.0006x over previous
.LBB0_432:
	s_ashr_i32 s15, s14, 31
	s_lshl_b64 s[38:39], s[14:15], 19
	s_add_u32 s38, s46, s38
	v_cmp_lt_i64_e64 s[28:29], s[28:29], 32
	s_addc_u32 s39, s47, s39
	s_and_b64 s[40:41], s[28:29], exec
	s_cselect_b32 s15, s39, s27
	s_cselect_b32 s76, s38, s26
	s_ashr_i32 s17, s16, 31
	s_lshl_b64 s[40:41], s[16:17], 19
	s_add_u32 s40, s48, s40
	s_addc_u32 s41, s49, s41
	s_and_b64 s[28:29], s[28:29], exec
	s_cselect_b32 s17, s41, s25
	s_cselect_b32 s28, s40, s24
	s_add_u32 s44, s26, 0x40080
	s_addc_u32 s45, s27, 0
	s_add_u32 s29, s24, 0x100
	v_mov_b32_e32 v0, 0
	s_addc_u32 s77, s25, 0
	s_mov_b32 s78, -2
	v_mov_b64_e32 v[0:1], 0
	v_mov_b64_e32 v[2:3], 0
	v_mov_b64_e32 v[4:5], 0
	v_mov_b64_e32 v[6:7], 0
	v_mov_b64_e32 v[8:9], 0
	v_mov_b64_e32 v[10:11], 0
	v_mov_b64_e32 v[12:13], 0
	v_mov_b64_e32 v[14:15], 0
	v_mov_b64_e32 v[16:17], 0
	v_mov_b64_e32 v[18:19], 0
	v_mov_b64_e32 v[20:21], 0
	v_mov_b64_e32 v[22:23], 0
	v_mov_b64_e32 v[24:25], 0
	v_mov_b64_e32 v[26:27], 0
	v_mov_b64_e32 v[28:29], 0
	v_mov_b64_e32 v[30:31], 0
	v_mov_b64_e32 v[32:33], 0
	v_mov_b64_e32 v[34:35], 0
	v_mov_b64_e32 v[36:37], 0
	v_mov_b64_e32 v[38:39], 0
	v_mov_b64_e32 v[40:41], 0
	v_mov_b64_e32 v[42:43], 0
	v_mov_b64_e32 v[44:45], 0
	v_mov_b64_e32 v[46:47], 0
	v_mov_b64_e32 v[48:49], 0
	v_mov_b64_e32 v[50:51], 0
	v_mov_b64_e32 v[52:53], 0
	v_mov_b64_e32 v[54:55], 0
	v_mov_b64_e32 v[56:57], 0
	v_mov_b64_e32 v[58:59], 0
	v_mov_b64_e32 v[60:61], 0
	v_mov_b64_e32 v[62:63], 0
	v_mov_b64_e32 v[64:65], 0
	v_mov_b64_e32 v[66:67], 0
	v_mov_b64_e32 v[68:69], 0
	v_mov_b64_e32 v[70:71], 0
	v_mov_b64_e32 v[72:73], 0
	v_mov_b64_e32 v[74:75], 0
	v_mov_b64_e32 v[76:77], 0
	v_mov_b64_e32 v[78:79], 0
	v_mov_b64_e32 v[80:81], 0
	v_mov_b64_e32 v[82:83], 0
	v_mov_b64_e32 v[84:85], 0
	v_mov_b64_e32 v[86:87], 0
	v_mov_b64_e32 v[88:89], 0
	v_mov_b64_e32 v[90:91], 0
	v_mov_b64_e32 v[92:93], 0
	v_mov_b64_e32 v[94:95], 0
	v_mov_b64_e32 v[96:97], 0
	v_mov_b64_e32 v[98:99], 0
	v_mov_b64_e32 v[100:101], 0
	v_mov_b64_e32 v[102:103], 0
	v_mov_b64_e32 v[104:105], 0
	v_mov_b64_e32 v[106:107], 0
	v_mov_b64_e32 v[108:109], 0
	v_mov_b64_e32 v[110:111], 0
	v_mov_b64_e32 v[112:113], 0
	v_mov_b64_e32 v[114:115], 0
	v_mov_b64_e32 v[116:117], 0
	v_mov_b64_e32 v[118:119], 0
	v_mov_b64_e32 v[120:121], 0
	v_mov_b64_e32 v[122:123], 0
	v_mov_b64_e32 v[124:125], 0
	v_mov_b64_e32 v[126:127], 0

.LBB0_1091:
	s_ashr_i32 s27, s26, 31
	v_cmp_lt_i64_e32 vcc, s[38:39], v[156:157]
	s_lshl_b64 s[38:39], s[26:27], 19
	s_add_u32 s38, s48, s38
	s_addc_u32 s39, s49, s39
	s_and_b64 s[40:41], vcc, exec
	s_cselect_b32 s27, s39, s31
	s_cselect_b32 s72, s38, s30
	s_ashr_i32 s25, s24, 31
	s_lshl_b64 s[40:41], s[24:25], 19
	s_add_u32 s40, s52, s40
	s_addc_u32 s41, s53, s41
	s_and_b64 s[44:45], vcc, exec
	s_cselect_b32 s25, s41, s29
	s_cselect_b32 s73, s40, s28
	s_add_u32 s44, s30, 0x40080
	s_addc_u32 s45, s31, 0
	s_add_u32 s74, s28, 0x100
	v_mov_b32_e32 v0, 0
	s_addc_u32 s75, s29, 0
	s_mov_b32 s76, -2
	v_mov_b64_e32 v[0:1], 0
	v_mov_b64_e32 v[2:3], 0
	v_mov_b64_e32 v[4:5], 0
	v_mov_b64_e32 v[6:7], 0
	v_mov_b64_e32 v[8:9], 0
	v_mov_b64_e32 v[10:11], 0
	v_mov_b64_e32 v[12:13], 0
	v_mov_b64_e32 v[14:15], 0
	v_mov_b64_e32 v[16:17], 0
	v_mov_b64_e32 v[18:19], 0
	v_mov_b64_e32 v[20:21], 0
	v_mov_b64_e32 v[22:23], 0
	v_mov_b64_e32 v[24:25], 0
	v_mov_b64_e32 v[26:27], 0
	v_mov_b64_e32 v[28:29], 0
	v_mov_b64_e32 v[30:31], 0
	v_mov_b64_e32 v[32:33], 0
	v_mov_b64_e32 v[34:35], 0
	v_mov_b64_e32 v[36:37], 0
	v_mov_b64_e32 v[38:39], 0
	v_mov_b64_e32 v[40:41], 0
	v_mov_b64_e32 v[42:43], 0
	v_mov_b64_e32 v[44:45], 0
	v_mov_b64_e32 v[46:47], 0
	v_mov_b64_e32 v[48:49], 0
	v_mov_b64_e32 v[50:51], 0
	v_mov_b64_e32 v[52:53], 0
	v_mov_b64_e32 v[54:55], 0
	v_mov_b64_e32 v[56:57], 0
	v_mov_b64_e32 v[58:59], 0
	v_mov_b64_e32 v[60:61], 0
	v_mov_b64_e32 v[62:63], 0
	v_mov_b64_e32 v[64:65], 0
	v_mov_b64_e32 v[66:67], 0
	v_mov_b64_e32 v[68:69], 0
	v_mov_b64_e32 v[70:71], 0
	v_mov_b64_e32 v[72:73], 0
	v_mov_b64_e32 v[74:75], 0
	v_mov_b64_e32 v[76:77], 0
	v_mov_b64_e32 v[78:79], 0
	v_mov_b64_e32 v[80:81], 0
	v_mov_b64_e32 v[82:83], 0
	v_mov_b64_e32 v[84:85], 0
	v_mov_b64_e32 v[86:87], 0
	v_mov_b64_e32 v[88:89], 0
	v_mov_b64_e32 v[90:91], 0
	v_mov_b64_e32 v[92:93], 0
	v_mov_b64_e32 v[94:95], 0
	v_mov_b64_e32 v[96:97], 0
	v_mov_b64_e32 v[98:99], 0
	v_mov_b64_e32 v[100:101], 0
	v_mov_b64_e32 v[102:103], 0
	v_mov_b64_e32 v[104:105], 0
	v_mov_b64_e32 v[106:107], 0
	v_mov_b64_e32 v[108:109], 0
	v_mov_b64_e32 v[110:111], 0
	v_mov_b64_e32 v[112:113], 0
	v_mov_b64_e32 v[114:115], 0
	v_mov_b64_e32 v[116:117], 0
	v_mov_b64_e32 v[118:119], 0
	v_mov_b64_e32 v[120:121], 0
	v_mov_b64_e32 v[122:123], 0
	v_mov_b64_e32 v[124:125], 0
	v_mov_b64_e32 v[126:127], 0

.LBB0_1243:
	s_ashr_i32 s13, s12, 31
	v_cmp_lt_i64_e32 vcc, s[14:15], v[140:141]
	s_lshl_b64 s[14:15], s[12:13], 19
	s_add_u32 s14, s39, s14
	s_addc_u32 s15, s40, s15
	s_and_b64 s[16:17], vcc, exec
	s_cselect_b32 s13, s15, s27
	s_cselect_b32 s58, s14, s26
	s_ashr_i32 s11, s10, 31
	s_lshl_b64 s[16:17], s[10:11], 19
	s_add_u32 s16, s41, s16
	s_addc_u32 s17, s42, s17
	s_and_b64 s[30:31], vcc, exec
	s_cselect_b32 s11, s17, s29
	s_cselect_b32 s59, s16, s28
	s_add_u32 s26, s26, 0x40080
	s_addc_u32 s27, s27, 0
	s_add_u32 s60, s28, 0x100
	v_mov_b32_e32 v0, 0
	s_addc_u32 s61, s29, 0
	s_mov_b32 s62, -2
	v_mov_b64_e32 v[0:1], 0
	v_mov_b64_e32 v[2:3], 0
	v_mov_b64_e32 v[4:5], 0
	v_mov_b64_e32 v[6:7], 0
	v_mov_b64_e32 v[8:9], 0
	v_mov_b64_e32 v[10:11], 0
	v_mov_b64_e32 v[12:13], 0
	v_mov_b64_e32 v[14:15], 0
	v_mov_b64_e32 v[16:17], 0
	v_mov_b64_e32 v[18:19], 0
	v_mov_b64_e32 v[20:21], 0
	v_mov_b64_e32 v[22:23], 0
	v_mov_b64_e32 v[24:25], 0
	v_mov_b64_e32 v[26:27], 0
	v_mov_b64_e32 v[28:29], 0
	v_mov_b64_e32 v[30:31], 0
	v_mov_b64_e32 v[32:33], 0
	v_mov_b64_e32 v[34:35], 0
	v_mov_b64_e32 v[36:37], 0
	v_mov_b64_e32 v[38:39], 0
	v_mov_b64_e32 v[40:41], 0
	v_mov_b64_e32 v[42:43], 0
	v_mov_b64_e32 v[44:45], 0
	v_mov_b64_e32 v[46:47], 0
	v_mov_b64_e32 v[48:49], 0
	v_mov_b64_e32 v[50:51], 0
	v_mov_b64_e32 v[52:53], 0
	v_mov_b64_e32 v[54:55], 0
	v_mov_b64_e32 v[56:57], 0
	v_mov_b64_e32 v[58:59], 0
	v_mov_b64_e32 v[60:61], 0
	v_mov_b64_e32 v[62:63], 0
	v_mov_b64_e32 v[64:65], 0
	v_mov_b64_e32 v[66:67], 0
	v_mov_b64_e32 v[68:69], 0
	v_mov_b64_e32 v[70:71], 0
	v_mov_b64_e32 v[72:73], 0
	v_mov_b64_e32 v[74:75], 0
	v_mov_b64_e32 v[76:77], 0
	v_mov_b64_e32 v[78:79], 0
	v_mov_b64_e32 v[80:81], 0
	v_mov_b64_e32 v[82:83], 0
	v_mov_b64_e32 v[84:85], 0
	v_mov_b64_e32 v[86:87], 0
	v_mov_b64_e32 v[88:89], 0
	v_mov_b64_e32 v[90:91], 0
	v_mov_b64_e32 v[92:93], 0
	v_mov_b64_e32 v[94:95], 0
	v_mov_b64_e32 v[96:97], 0
	v_mov_b64_e32 v[98:99], 0
	v_mov_b64_e32 v[100:101], 0
	v_mov_b64_e32 v[102:103], 0
	v_mov_b64_e32 v[104:105], 0
	v_mov_b64_e32 v[106:107], 0
	v_mov_b64_e32 v[108:109], 0
	v_mov_b64_e32 v[110:111], 0
	v_mov_b64_e32 v[112:113], 0
	v_mov_b64_e32 v[114:115], 0
	v_mov_b64_e32 v[116:117], 0
	v_mov_b64_e32 v[118:119], 0
	v_mov_b64_e32 v[120:121], 0
	v_mov_b64_e32 v[122:123], 0
	v_mov_b64_e32 v[124:125], 0
	v_mov_b64_e32 v[126:127], 0

.LBB0_1322:
	s_add_u32 s26, s26, 0xb0080
	s_addc_u32 s27, s27, 0
	s_add_u32 s66, s28, 0x100
	v_mov_b32_e32 v0, 0
	s_addc_u32 s67, s29, 0
	s_mov_b32 s68, -2
	v_mov_b64_e32 v[0:1], 0
	v_mov_b64_e32 v[2:3], 0
	v_mov_b64_e32 v[4:5], 0
	v_mov_b64_e32 v[6:7], 0
	v_mov_b64_e32 v[8:9], 0
	v_mov_b64_e32 v[10:11], 0
	v_mov_b64_e32 v[12:13], 0
	v_mov_b64_e32 v[14:15], 0
	v_mov_b64_e32 v[16:17], 0
	v_mov_b64_e32 v[18:19], 0
	v_mov_b64_e32 v[20:21], 0
	v_mov_b64_e32 v[22:23], 0
	v_mov_b64_e32 v[24:25], 0
	v_mov_b64_e32 v[26:27], 0
	v_mov_b64_e32 v[28:29], 0
	v_mov_b64_e32 v[30:31], 0
	v_mov_b64_e32 v[32:33], 0
	v_mov_b64_e32 v[34:35], 0
	v_mov_b64_e32 v[36:37], 0
	v_mov_b64_e32 v[38:39], 0
	v_mov_b64_e32 v[40:41], 0
	v_mov_b64_e32 v[42:43], 0
	v_mov_b64_e32 v[44:45], 0
	v_mov_b64_e32 v[46:47], 0
	v_mov_b64_e32 v[48:49], 0
	v_mov_b64_e32 v[50:51], 0
	v_mov_b64_e32 v[52:53], 0
	v_mov_b64_e32 v[54:55], 0
	v_mov_b64_e32 v[56:57], 0
	v_mov_b64_e32 v[58:59], 0
	v_mov_b64_e32 v[60:61], 0
	v_mov_b64_e32 v[62:63], 0
	v_mov_b64_e32 v[64:65], 0
	v_mov_b64_e32 v[66:67], 0
	v_mov_b64_e32 v[68:69], 0
	v_mov_b64_e32 v[70:71], 0
	v_mov_b64_e32 v[72:73], 0
	v_mov_b64_e32 v[74:75], 0
	v_mov_b64_e32 v[76:77], 0
	v_mov_b64_e32 v[78:79], 0
	v_mov_b64_e32 v[80:81], 0
	v_mov_b64_e32 v[82:83], 0
	v_mov_b64_e32 v[84:85], 0
	v_mov_b64_e32 v[86:87], 0
	v_mov_b64_e32 v[88:89], 0
	v_mov_b64_e32 v[90:91], 0
	v_mov_b64_e32 v[92:93], 0
	v_mov_b64_e32 v[94:95], 0
	v_mov_b64_e32 v[96:97], 0
	v_mov_b64_e32 v[98:99], 0
	v_mov_b64_e32 v[100:101], 0
	v_mov_b64_e32 v[102:103], 0
	v_mov_b64_e32 v[104:105], 0
	v_mov_b64_e32 v[106:107], 0
	v_mov_b64_e32 v[108:109], 0
	v_mov_b64_e32 v[110:111], 0
	v_mov_b64_e32 v[112:113], 0
	v_mov_b64_e32 v[114:115], 0
	v_mov_b64_e32 v[116:117], 0
	v_mov_b64_e32 v[118:119], 0
	v_mov_b64_e32 v[120:121], 0
	v_mov_b64_e32 v[122:123], 0
	v_mov_b64_e32 v[124:125], 0
	v_mov_b64_e32 v[126:127], 0
